# SwiGLU epilogues: r^2 folded into the reciprocal argument, one packed multiply less per output pair (f32 math, same formula up to rounding order)
# baseline (speedup 1.0000x reference)
; __device__ __forceinline__ float silu1(float g) { return g * __builtin_amdgcn_rcpf(1.0f + __expf(-g)); }
; __device__ __forceinline__ f32x4 swiglu4(f32x4 g, f32x4 u) { return (f32x4){silu1(g[0]) * u[0], silu1(g[1]) * u[1], silu1(g[2]) * u[2], silu1(g[3]) * u[3]}; }
; template <int EK>
; __device__ __forceinline__ void epi_tile(const f32x4 (&acc)[2][2][4][2], const Unit& u, int wr, int wc, int fr, int fq, const EpiArgs& E, const LAS float* rt) {
;     const int rowb = u.pm * BM + wr * 64 + fr;
;     float rr[2][4];
;     if (EK != EK_RES) {
; #pragma unroll
;         for (int ai = 0; ai < 2; ++ai)
; #pragma unroll
;             for (int m = 0; m < 4; ++m) rr[ai][m] = rt[ai * HALF + wr * 64 + m * 16 + fr];
;     }
; #pragma unroll
;     for (int ai = 0; ai < 2; ++ai) {
; #pragma unroll
;         for (int m = 0; m < 4; ++m) {
;             const int row = rowb + ai * HALF + m * 16;
;             if (EK == EK_SCALE) {
;                 const float r = rr[ai][m];
; #pragma unroll
;                 for (int bj = 0; bj < 2; ++bj) { const int col = u.pn * BM + bj * HALF + wc * 32 + fq * 8;
;                     const u32x2 lo = pack4(acc[ai][bj][m][0] * r), hi = pack4(acc[ai][bj][m][1] * r);
;                     *(u32x4*)(E.ob + (size_t)row * E.ldb + col) = (u32x4){lo.x, lo.y, hi.x, hi.y}; }
;             } else if (EK == EK_GELU) {
;                 const float r = rr[ai][m]; float ss = 0.f;
; #pragma unroll
;                 for (int bj = 0; bj < 2; ++bj) { const int col = u.pn * BM + bj * HALF + wc * 32 + fq * 8;
;                     const f32x4 z0 = gelu4(acc[ai][bj][m][0] * r), z1 = gelu4(acc[ai][bj][m][1] * r); ss += dot4(z0) + dot4(z1);
;                     const u32x2 lo = pack4(z0), hi = pack4(z1);
;                     *(u32x4*)(E.ob + (size_t)row * E.ldb + col) = (u32x4){lo.x, lo.y, hi.x, hi.y}; }
;                 if (u.pn >= 4) { ss = quad_sum(ss); if (fq == 0) E.stOut[(size_t)row * 16 + (u.pn - 4) * 4 + wc] = ss; }
;             } else if (EK == EK_SWIGLU) {
;                 const float r = rr[ai][m];
;                 { const int col = u.pn * HALF + wc * 32 + fq * 8;
;                     const u32x2 lo = pack4(swiglu4(acc[ai][0][m][0] * r, acc[ai][1][m][0] * r)), hi = pack4(swiglu4(acc[ai][0][m][1] * r, acc[ai][1][m][1] * r));
;                     *(u32x4*)(E.ob + (size_t)row * DFF + col) = (u32x4){lo.x, lo.y, hi.x, hi.y}; }
.LBB0_541:
	v_lshl_add_u32 v146, s52, 10, v160
	ds_read2_b32 v[168:169], v146 offset1:16
	ds_read2_b32 v[154:155], v146 offset0:32 offset1:48
	ds_read2_b32 v[152:153], v146 offset0:128 offset1:144
	ds_read2_b32 v[146:147], v146 offset0:160 offset1:176
	v_lshl_or_b32 v150, s14, 7, v161
	s_waitcnt lgkmcnt(0)
	v_mul_f32_e32 v180, 0xbfb8aa3b, v168
	v_mul_f32_e32 v181, v168, v168
	v_rcp_f32_e32 v181, v181
	v_mul_f32_e32 v182, 0xbfb8aa3b, v169
	v_mul_f32_e32 v183, v169, v169
	v_rcp_f32_e32 v183, v183
	v_mul_f32_e32 v184, 0xbfb8aa3b, v154
	v_mul_f32_e32 v185, v154, v154
	v_rcp_f32_e32 v185, v185
	v_mul_f32_e32 v186, 0xbfb8aa3b, v155
	v_mul_f32_e32 v187, v155, v155
	v_rcp_f32_e32 v187, v187
	v_mul_f32_e32 v188, 0xbfb8aa3b, v152
	v_mul_f32_e32 v189, v152, v152
	v_rcp_f32_e32 v189, v189
	v_mul_f32_e32 v190, 0xbfb8aa3b, v153
	v_mul_f32_e32 v191, v153, v153
	v_rcp_f32_e32 v191, v191
	v_mul_f32_e32 v192, 0xbfb8aa3b, v146
	v_mul_f32_e32 v193, v146, v146
	v_rcp_f32_e32 v193, v193
	v_mul_f32_e32 v194, 0xbfb8aa3b, v147
	v_mul_f32_e32 v195, v147, v147
	v_rcp_f32_e32 v195, v195
	s_add_u32 s74, s54, 0xffffff00
	v_lshl_add_u32 v163, s16, 8, v158
	v_ashrrev_i32_e32 v151, 31, v150
	s_addc_u32 s75, s55, -1
	v_mov_b64_e32 v[148:149], s[64:65]
	v_mad_i64_i32 v[170:171], s[54:55], v163, s90, v[148:149]
	v_lshlrev_b64 v[150:151], 1, v[150:151]
	v_lshl_add_u64 v[170:171], v[170:171], 0, v[150:151]
	v_pk_mul_f32 v[196:197], v[110:111], v[180:181] op_sel_hi:[1,0]
	v_pk_mul_f32 v[198:199], v[112:113], v[180:181] op_sel_hi:[1,0]
	v_pk_mul_f32 v[200:201], v[110:111], v[78:79]
	v_exp_f32_e32 v196, v196
	v_exp_f32_e32 v197, v197
	v_exp_f32_e32 v198, v198
	v_exp_f32_e32 v199, v199
	v_pk_mul_f32 v[202:203], v[112:113], v[80:81]
	v_pk_fma_f32 v[196:197], v[196:197], v[180:181], v[180:181] op_sel:[0,1,1] op_sel_hi:[1,1,1]
	v_pk_fma_f32 v[198:199], v[198:199], v[180:181], v[180:181] op_sel:[0,1,1] op_sel_hi:[1,1,1]
	v_rcp_f32_e32 v196, v196
	v_rcp_f32_e32 v197, v197
	v_rcp_f32_e32 v198, v198
	v_rcp_f32_e32 v199, v199
	v_pk_mul_f32 v[200:201], v[200:201], v[196:197]
	v_pk_mul_f32 v[202:203], v[202:203], v[198:199]
	v_cvt_pk_bf16_f32 v204, v200, v201
	v_cvt_pk_bf16_f32 v205, v202, v203
	v_pk_mul_f32 v[196:197], v[106:107], v[180:181] op_sel_hi:[1,0]
	v_pk_mul_f32 v[198:199], v[108:109], v[180:181] op_sel_hi:[1,0]
	v_pk_mul_f32 v[200:201], v[106:107], v[74:75]
	v_exp_f32_e32 v196, v196
	v_exp_f32_e32 v197, v197
	v_exp_f32_e32 v198, v198
	v_exp_f32_e32 v199, v199
	v_pk_mul_f32 v[202:203], v[108:109], v[76:77]
	v_pk_fma_f32 v[196:197], v[196:197], v[180:181], v[180:181] op_sel:[0,1,1] op_sel_hi:[1,1,1]
	v_pk_fma_f32 v[198:199], v[198:199], v[180:181], v[180:181] op_sel:[0,1,1] op_sel_hi:[1,1,1]
	v_rcp_f32_e32 v196, v196
	v_rcp_f32_e32 v197, v197
	v_rcp_f32_e32 v198, v198
	v_rcp_f32_e32 v199, v199
	v_pk_mul_f32 v[200:201], v[200:201], v[196:197]
	v_pk_mul_f32 v[202:203], v[202:203], v[198:199]
	v_cvt_pk_bf16_f32 v206, v200, v201
	v_cvt_pk_bf16_f32 v207, v202, v203
	global_store_dwordx4 v[170:171], v[204:207], off
	v_or_b32_e32 v174, 16, v163
	s_andn2_b64 vcc, exec, s[6:7]
	v_mad_i64_i32 v[168:169], s[54:55], v174, s90, v[148:149]
	v_lshl_add_u64 v[168:169], v[168:169], 0, v[150:151]
	v_pk_mul_f32 v[196:197], v[102:103], v[182:183] op_sel_hi:[1,0]
	v_pk_mul_f32 v[198:199], v[104:105], v[182:183] op_sel_hi:[1,0]
	v_pk_mul_f32 v[200:201], v[102:103], v[70:71]
	v_exp_f32_e32 v196, v196
	v_exp_f32_e32 v197, v197
	v_exp_f32_e32 v198, v198
	v_exp_f32_e32 v199, v199
	v_pk_mul_f32 v[202:203], v[104:105], v[72:73]
	v_pk_fma_f32 v[196:197], v[196:197], v[182:183], v[182:183] op_sel:[0,1,1] op_sel_hi:[1,1,1]
	v_pk_fma_f32 v[198:199], v[198:199], v[182:183], v[182:183] op_sel:[0,1,1] op_sel_hi:[1,1,1]
	v_rcp_f32_e32 v196, v196
	v_rcp_f32_e32 v197, v197
	v_rcp_f32_e32 v198, v198
	v_rcp_f32_e32 v199, v199
	v_pk_mul_f32 v[200:201], v[200:201], v[196:197]
	v_pk_mul_f32 v[202:203], v[202:203], v[198:199]
	v_cvt_pk_bf16_f32 v208, v200, v201
	v_cvt_pk_bf16_f32 v209, v202, v203
	v_pk_mul_f32 v[196:197], v[98:99], v[182:183] op_sel_hi:[1,0]
	v_pk_mul_f32 v[198:199], v[100:101], v[182:183] op_sel_hi:[1,0]
	v_pk_mul_f32 v[200:201], v[98:99], v[66:67]
	v_exp_f32_e32 v196, v196
	v_exp_f32_e32 v197, v197
	v_exp_f32_e32 v198, v198
	v_exp_f32_e32 v199, v199
	v_pk_mul_f32 v[202:203], v[100:101], v[68:69]
	v_pk_fma_f32 v[196:197], v[196:197], v[182:183], v[182:183] op_sel:[0,1,1] op_sel_hi:[1,1,1]
	v_pk_fma_f32 v[198:199], v[198:199], v[182:183], v[182:183] op_sel:[0,1,1] op_sel_hi:[1,1,1]
	v_rcp_f32_e32 v196, v196
	v_rcp_f32_e32 v197, v197
	v_rcp_f32_e32 v198, v198
	v_rcp_f32_e32 v199, v199
	v_pk_mul_f32 v[200:201], v[200:201], v[196:197]
	v_pk_mul_f32 v[202:203], v[202:203], v[198:199]
	v_cvt_pk_bf16_f32 v210, v200, v201
	v_cvt_pk_bf16_f32 v211, v202, v203
	global_store_dwordx4 v[168:169], v[208:211], off
	v_or_b32_e32 v174, 32, v163
	v_mad_i64_i32 v[168:169], s[54:55], v174, s90, v[148:149]
	v_lshl_add_u64 v[168:169], v[168:169], 0, v[150:151]
	v_pk_mul_f32 v[196:197], v[94:95], v[184:185] op_sel_hi:[1,0]
	v_pk_mul_f32 v[198:199], v[96:97], v[184:185] op_sel_hi:[1,0]
	v_pk_mul_f32 v[200:201], v[94:95], v[62:63]
	v_exp_f32_e32 v196, v196
	v_exp_f32_e32 v197, v197
	v_exp_f32_e32 v198, v198
	v_exp_f32_e32 v199, v199
	v_pk_mul_f32 v[202:203], v[96:97], v[64:65]
	v_pk_fma_f32 v[196:197], v[196:197], v[184:185], v[184:185] op_sel:[0,1,1] op_sel_hi:[1,1,1]
	v_pk_fma_f32 v[198:199], v[198:199], v[184:185], v[184:185] op_sel:[0,1,1] op_sel_hi:[1,1,1]
	v_rcp_f32_e32 v196, v196
	v_rcp_f32_e32 v197, v197
	v_rcp_f32_e32 v198, v198
	v_rcp_f32_e32 v199, v199
	v_pk_mul_f32 v[200:201], v[200:201], v[196:197]
; __device__ __forceinline__ u32x2 pack4(f32x4 v) { u32x2 w; w.x = cvt_pk_bf16(v[0], v[1]); w.y = cvt_pk_bf16(v[2], v[3]); return w; }
; __device__ __forceinline__ float silu1(float g) { return g * __builtin_amdgcn_rcpf(1.0f + __expf(-g)); }
; __device__ __forceinline__ f32x4 swiglu4(f32x4 g, f32x4 u) { return (f32x4){silu1(g[0]) * u[0], silu1(g[1]) * u[1], silu1(g[2]) * u[2], silu1(g[3]) * u[3]}; }
; template <int EK>
; __device__ __forceinline__ void epi_tile(const f32x4 (&acc)[2][2][4][2], const Unit& u, int wr, int wc, int fr, int fq, const EpiArgs& E, const LAS float* rt) {
;     ...
;             } else if (EK == EK_SWIGLU) {
;                 const float r = rr[ai][m];
;                 { const int col = u.pn * HALF + wc * 32 + fq * 8;
;                     const u32x2 lo = pack4(swiglu4(acc[ai][0][m][0] * r, acc[ai][1][m][0] * r)), hi = pack4(swiglu4(acc[ai][0][m][1] * r, acc[ai][1][m][1] * r));
;                     *(u32x4*)(E.ob + (size_t)row * DFF + col) = (u32x4){lo.x, lo.y, hi.x, hi.y}; }
	v_pk_mul_f32 v[202:203], v[202:203], v[198:199]
	v_cvt_pk_bf16_f32 v204, v200, v201
	v_cvt_pk_bf16_f32 v205, v202, v203
	v_pk_mul_f32 v[196:197], v[90:91], v[184:185] op_sel_hi:[1,0]
	v_pk_mul_f32 v[198:199], v[92:93], v[184:185] op_sel_hi:[1,0]
	v_pk_mul_f32 v[200:201], v[90:91], v[58:59]
	v_exp_f32_e32 v196, v196
	v_exp_f32_e32 v197, v197
	v_exp_f32_e32 v198, v198
	v_exp_f32_e32 v199, v199
	v_pk_mul_f32 v[202:203], v[92:93], v[60:61]
	v_pk_fma_f32 v[196:197], v[196:197], v[184:185], v[184:185] op_sel:[0,1,1] op_sel_hi:[1,1,1]
	v_pk_fma_f32 v[198:199], v[198:199], v[184:185], v[184:185] op_sel:[0,1,1] op_sel_hi:[1,1,1]
	v_rcp_f32_e32 v196, v196
	v_rcp_f32_e32 v197, v197
	v_rcp_f32_e32 v198, v198
	v_rcp_f32_e32 v199, v199
	v_pk_mul_f32 v[200:201], v[200:201], v[196:197]
	v_pk_mul_f32 v[202:203], v[202:203], v[198:199]
	v_cvt_pk_bf16_f32 v206, v200, v201
	v_cvt_pk_bf16_f32 v207, v202, v203
	global_store_dwordx4 v[168:169], v[204:207], off
	v_or_b32_e32 v172, 48, v163
	v_mad_i64_i32 v[154:155], s[54:55], v172, s90, v[148:149]
	v_lshl_add_u64 v[154:155], v[154:155], 0, v[150:151]
	v_pk_mul_f32 v[196:197], v[86:87], v[186:187] op_sel_hi:[1,0]
	v_pk_mul_f32 v[198:199], v[88:89], v[186:187] op_sel_hi:[1,0]
	v_pk_mul_f32 v[200:201], v[86:87], v[54:55]
	v_exp_f32_e32 v196, v196
	v_exp_f32_e32 v197, v197
	v_exp_f32_e32 v198, v198
	v_exp_f32_e32 v199, v199
	v_pk_mul_f32 v[202:203], v[88:89], v[56:57]
	v_pk_fma_f32 v[196:197], v[196:197], v[186:187], v[186:187] op_sel:[0,1,1] op_sel_hi:[1,1,1]
	v_pk_fma_f32 v[198:199], v[198:199], v[186:187], v[186:187] op_sel:[0,1,1] op_sel_hi:[1,1,1]
	v_rcp_f32_e32 v196, v196
	v_rcp_f32_e32 v197, v197
	v_rcp_f32_e32 v198, v198
	v_rcp_f32_e32 v199, v199
	v_pk_mul_f32 v[200:201], v[200:201], v[196:197]
	v_pk_mul_f32 v[202:203], v[202:203], v[198:199]
	v_cvt_pk_bf16_f32 v208, v200, v201
	v_cvt_pk_bf16_f32 v209, v202, v203
	v_pk_mul_f32 v[196:197], v[82:83], v[186:187] op_sel_hi:[1,0]
	v_pk_mul_f32 v[198:199], v[84:85], v[186:187] op_sel_hi:[1,0]
	v_pk_mul_f32 v[200:201], v[82:83], v[50:51]
	v_exp_f32_e32 v196, v196
	v_exp_f32_e32 v197, v197
	v_exp_f32_e32 v198, v198
	v_exp_f32_e32 v199, v199
	v_pk_mul_f32 v[202:203], v[84:85], v[52:53]
	v_pk_fma_f32 v[196:197], v[196:197], v[186:187], v[186:187] op_sel:[0,1,1] op_sel_hi:[1,1,1]
	v_pk_fma_f32 v[198:199], v[198:199], v[186:187], v[186:187] op_sel:[0,1,1] op_sel_hi:[1,1,1]
	v_rcp_f32_e32 v196, v196
	v_rcp_f32_e32 v197, v197
	v_rcp_f32_e32 v198, v198
	v_rcp_f32_e32 v199, v199
	v_pk_mul_f32 v[200:201], v[200:201], v[196:197]
	v_pk_mul_f32 v[202:203], v[202:203], v[198:199]
	v_cvt_pk_bf16_f32 v210, v200, v201
	v_cvt_pk_bf16_f32 v211, v202, v203
	global_store_dwordx4 v[154:155], v[208:211], off
	v_add_u32_e32 v172, 0x80, v163
	v_mad_i64_i32 v[154:155], s[54:55], v172, s90, v[148:149]
	v_lshl_add_u64 v[154:155], v[154:155], 0, v[150:151]
	v_pk_mul_f32 v[196:197], v[46:47], v[188:189] op_sel_hi:[1,0]
	v_pk_mul_f32 v[198:199], v[48:49], v[188:189] op_sel_hi:[1,0]
	v_pk_mul_f32 v[200:201], v[46:47], v[14:15]
	v_exp_f32_e32 v196, v196
	v_exp_f32_e32 v197, v197
	v_exp_f32_e32 v198, v198
	v_exp_f32_e32 v199, v199
	v_pk_mul_f32 v[202:203], v[48:49], v[16:17]
	v_pk_fma_f32 v[196:197], v[196:197], v[188:189], v[188:189] op_sel:[0,1,1] op_sel_hi:[1,1,1]
	v_pk_fma_f32 v[198:199], v[198:199], v[188:189], v[188:189] op_sel:[0,1,1] op_sel_hi:[1,1,1]
	v_rcp_f32_e32 v196, v196
	v_rcp_f32_e32 v197, v197
	v_rcp_f32_e32 v198, v198
	v_rcp_f32_e32 v199, v199
	v_pk_mul_f32 v[200:201], v[200:201], v[196:197]
	v_pk_mul_f32 v[202:203], v[202:203], v[198:199]
	v_cvt_pk_bf16_f32 v204, v200, v201
	v_cvt_pk_bf16_f32 v205, v202, v203
	v_pk_mul_f32 v[196:197], v[42:43], v[188:189] op_sel_hi:[1,0]
	v_pk_mul_f32 v[198:199], v[44:45], v[188:189] op_sel_hi:[1,0]
	v_pk_mul_f32 v[200:201], v[42:43], v[10:11]
	v_exp_f32_e32 v196, v196
	v_exp_f32_e32 v197, v197
	v_exp_f32_e32 v198, v198
	v_exp_f32_e32 v199, v199
	v_pk_mul_f32 v[202:203], v[44:45], v[12:13]
	v_pk_fma_f32 v[196:197], v[196:197], v[188:189], v[188:189] op_sel:[0,1,1] op_sel_hi:[1,1,1]
	v_pk_fma_f32 v[198:199], v[198:199], v[188:189], v[188:189] op_sel:[0,1,1] op_sel_hi:[1,1,1]
	v_rcp_f32_e32 v196, v196
	v_rcp_f32_e32 v197, v197
	v_rcp_f32_e32 v198, v198
	v_rcp_f32_e32 v199, v199
	v_pk_mul_f32 v[200:201], v[200:201], v[196:197]
	v_pk_mul_f32 v[202:203], v[202:203], v[198:199]
	v_cvt_pk_bf16_f32 v206, v200, v201
	v_cvt_pk_bf16_f32 v207, v202, v203
	global_store_dwordx4 v[154:155], v[204:207], off
	v_add_u32_e32 v170, 0x90, v163
	v_mad_i64_i32 v[164:165], s[54:55], v170, s90, v[148:149]
	v_lshl_add_u64 v[164:165], v[164:165], 0, v[150:151]
	v_pk_mul_f32 v[196:197], v[38:39], v[190:191] op_sel_hi:[1,0]
	v_pk_mul_f32 v[198:199], v[40:41], v[190:191] op_sel_hi:[1,0]
	v_pk_mul_f32 v[200:201], v[38:39], v[6:7]
	v_exp_f32_e32 v196, v196
	v_exp_f32_e32 v197, v197
	v_exp_f32_e32 v198, v198
	v_exp_f32_e32 v199, v199
	v_pk_mul_f32 v[202:203], v[40:41], v[8:9]
; __device__ __forceinline__ u32x2 pack4(f32x4 v) { u32x2 w; w.x = cvt_pk_bf16(v[0], v[1]); w.y = cvt_pk_bf16(v[2], v[3]); return w; }
; __device__ __forceinline__ f32x4 swiglu4(f32x4 g, f32x4 u) { return (f32x4){silu1(g[0]) * u[0], silu1(g[1]) * u[1], silu1(g[2]) * u[2], silu1(g[3]) * u[3]}; }
; #define PG8_BAR __builtin_amdgcn_s_barrier()
; template <int EK>
; __device__ __forceinline__ void epi_tile(const f32x4 (&acc)[2][2][4][2], const Unit& u, int wr, int wc, int fr, int fq, const EpiArgs& E, const LAS float* rt) {
;     ...
;             } else if (EK == EK_SWIGLU) {
;                 const float r = rr[ai][m];
;                 { const int col = u.pn * HALF + wc * 32 + fq * 8;
;                     const u32x2 lo = pack4(swiglu4(acc[ai][0][m][0] * r, acc[ai][1][m][0] * r)), hi = pack4(swiglu4(acc[ai][0][m][1] * r, acc[ai][1][m][1] * r));
;                     *(u32x4*)(E.ob + (size_t)row * DFF + col) = (u32x4){lo.x, lo.y, hi.x, hi.y}; }
; template <int EK, int SK = -1>
; __device__ __forceinline__ void gemm_phase(LAS unsigned char* lds, const bf16_t* A, const bf16_t* Bt, int nM, int N, int K, const EpiArgs& E) {
;     ...
;         if (!has_next) break;
; #pragma unroll
;         for (int a = 0; a < 2; ++a)
; #pragma unroll
;             for (int b = 0; b < 2; ++b)
; #pragma unroll
;                 for (int m = 0; m < 4; ++m)
; #pragma unroll
;                     for (int n = 0; n < 2; ++n) acc[a][b][m][n] = (f32x4){0.f, 0.f, 0.f, 0.f};
;         cur = nxt; cA = nA; cB = nB; ++ui;
;         if (wr == 1) PG8_BAR;
	v_pk_fma_f32 v[196:197], v[196:197], v[190:191], v[190:191] op_sel:[0,1,1] op_sel_hi:[1,1,1]
	v_pk_fma_f32 v[198:199], v[198:199], v[190:191], v[190:191] op_sel:[0,1,1] op_sel_hi:[1,1,1]
	v_rcp_f32_e32 v196, v196
	v_rcp_f32_e32 v197, v197
	v_rcp_f32_e32 v198, v198
	v_rcp_f32_e32 v199, v199
	v_pk_mul_f32 v[200:201], v[200:201], v[196:197]
	v_pk_mul_f32 v[202:203], v[202:203], v[198:199]
	v_cvt_pk_bf16_f32 v208, v200, v201
	v_cvt_pk_bf16_f32 v209, v202, v203
	v_pk_mul_f32 v[196:197], v[34:35], v[190:191] op_sel_hi:[1,0]
	v_pk_mul_f32 v[198:199], v[36:37], v[190:191] op_sel_hi:[1,0]
	v_pk_mul_f32 v[200:201], v[34:35], v[2:3]
	v_exp_f32_e32 v196, v196
	v_exp_f32_e32 v197, v197
	v_exp_f32_e32 v198, v198
	v_exp_f32_e32 v199, v199
	v_pk_mul_f32 v[202:203], v[36:37], v[4:5]
	v_pk_fma_f32 v[196:197], v[196:197], v[190:191], v[190:191] op_sel:[0,1,1] op_sel_hi:[1,1,1]
	v_pk_fma_f32 v[198:199], v[198:199], v[190:191], v[190:191] op_sel:[0,1,1] op_sel_hi:[1,1,1]
	v_rcp_f32_e32 v196, v196
	v_rcp_f32_e32 v197, v197
	v_rcp_f32_e32 v198, v198
	v_rcp_f32_e32 v199, v199
	v_pk_mul_f32 v[200:201], v[200:201], v[196:197]
	v_pk_mul_f32 v[202:203], v[202:203], v[198:199]
	v_cvt_pk_bf16_f32 v210, v200, v201
	v_cvt_pk_bf16_f32 v211, v202, v203
	global_store_dwordx4 v[164:165], v[208:211], off
	v_add_u32_e32 v170, 0xa0, v163
	v_add_u32_e32 v163, 0xb0, v163
	v_mad_i64_i32 v[164:165], s[54:55], v170, s90, v[148:149]
	v_lshl_add_u64 v[164:165], v[164:165], 0, v[150:151]
	v_pk_mul_f32 v[196:197], v[30:31], v[192:193] op_sel_hi:[1,0]
	v_pk_mul_f32 v[198:199], v[32:33], v[192:193] op_sel_hi:[1,0]
	v_pk_mul_f32 v[200:201], v[30:31], v[114:115]
	v_exp_f32_e32 v196, v196
	v_exp_f32_e32 v197, v197
	v_exp_f32_e32 v198, v198
	v_exp_f32_e32 v199, v199
	v_pk_mul_f32 v[202:203], v[32:33], v[116:117]
	v_pk_fma_f32 v[196:197], v[196:197], v[192:193], v[192:193] op_sel:[0,1,1] op_sel_hi:[1,1,1]
	v_pk_fma_f32 v[198:199], v[198:199], v[192:193], v[192:193] op_sel:[0,1,1] op_sel_hi:[1,1,1]
	v_rcp_f32_e32 v196, v196
	v_rcp_f32_e32 v197, v197
	v_rcp_f32_e32 v198, v198
	v_rcp_f32_e32 v199, v199
	v_pk_mul_f32 v[200:201], v[200:201], v[196:197]
	v_pk_mul_f32 v[202:203], v[202:203], v[198:199]
	v_cvt_pk_bf16_f32 v204, v200, v201
	v_cvt_pk_bf16_f32 v205, v202, v203
	v_pk_mul_f32 v[196:197], v[26:27], v[192:193] op_sel_hi:[1,0]
	v_pk_mul_f32 v[198:199], v[28:29], v[192:193] op_sel_hi:[1,0]
	v_pk_mul_f32 v[200:201], v[26:27], v[118:119]
	v_exp_f32_e32 v196, v196
	v_exp_f32_e32 v197, v197
	v_exp_f32_e32 v198, v198
	v_exp_f32_e32 v199, v199
	v_pk_mul_f32 v[202:203], v[28:29], v[120:121]
	v_pk_fma_f32 v[196:197], v[196:197], v[192:193], v[192:193] op_sel:[0,1,1] op_sel_hi:[1,1,1]
	v_pk_fma_f32 v[198:199], v[198:199], v[192:193], v[192:193] op_sel:[0,1,1] op_sel_hi:[1,1,1]
	v_rcp_f32_e32 v196, v196
	v_rcp_f32_e32 v197, v197
	v_rcp_f32_e32 v198, v198
	v_rcp_f32_e32 v199, v199
	v_pk_mul_f32 v[200:201], v[200:201], v[196:197]
	v_pk_mul_f32 v[202:203], v[202:203], v[198:199]
	v_cvt_pk_bf16_f32 v206, v200, v201
	v_cvt_pk_bf16_f32 v207, v202, v203
	global_store_dwordx4 v[164:165], v[204:207], off
	v_mad_i64_i32 v[146:147], s[54:55], v163, s90, v[148:149]
	v_lshl_add_u64 v[146:147], v[146:147], 0, v[150:151]
	v_pk_mul_f32 v[196:197], v[22:23], v[194:195] op_sel_hi:[1,0]
	v_pk_mul_f32 v[198:199], v[24:25], v[194:195] op_sel_hi:[1,0]
	v_pk_mul_f32 v[200:201], v[22:23], v[122:123]
	v_exp_f32_e32 v196, v196
	v_exp_f32_e32 v197, v197
	v_exp_f32_e32 v198, v198
	v_exp_f32_e32 v199, v199
	v_pk_mul_f32 v[202:203], v[24:25], v[124:125]
	v_pk_fma_f32 v[196:197], v[196:197], v[194:195], v[194:195] op_sel:[0,1,1] op_sel_hi:[1,1,1]
	v_pk_fma_f32 v[198:199], v[198:199], v[194:195], v[194:195] op_sel:[0,1,1] op_sel_hi:[1,1,1]
	v_rcp_f32_e32 v196, v196
	v_rcp_f32_e32 v197, v197
	v_rcp_f32_e32 v198, v198
	v_rcp_f32_e32 v199, v199
	v_pk_mul_f32 v[200:201], v[200:201], v[196:197]
	v_pk_mul_f32 v[202:203], v[202:203], v[198:199]
	v_cvt_pk_bf16_f32 v208, v200, v201
	v_cvt_pk_bf16_f32 v209, v202, v203
	v_pk_mul_f32 v[196:197], v[18:19], v[194:195] op_sel_hi:[1,0]
	v_pk_mul_f32 v[198:199], v[20:21], v[194:195] op_sel_hi:[1,0]
	v_pk_mul_f32 v[200:201], v[18:19], v[126:127]
	v_exp_f32_e32 v196, v196
	v_exp_f32_e32 v197, v197
	v_exp_f32_e32 v198, v198
	v_exp_f32_e32 v199, v199
	v_pk_mul_f32 v[202:203], v[20:21], v[128:129]
	v_pk_fma_f32 v[196:197], v[196:197], v[194:195], v[194:195] op_sel:[0,1,1] op_sel_hi:[1,1,1]
	v_pk_fma_f32 v[198:199], v[198:199], v[194:195], v[194:195] op_sel:[0,1,1] op_sel_hi:[1,1,1]
	v_rcp_f32_e32 v196, v196
	v_rcp_f32_e32 v197, v197
	v_rcp_f32_e32 v198, v198
	v_rcp_f32_e32 v199, v199
	v_pk_mul_f32 v[200:201], v[200:201], v[196:197]
	v_pk_mul_f32 v[202:203], v[202:203], v[198:199]
	v_cvt_pk_bf16_f32 v210, v200, v201
	v_cvt_pk_bf16_f32 v211, v202, v203
	global_store_dwordx4 v[146:147], v[208:211], off
	s_cbranch_vccnz .LBB0_544
	s_andn2_b64 vcc, exec, s[8:9]
	s_cbranch_vccnz .LBB0_530
	s_barrier
	s_branch .LBB0_530

; __device__ __forceinline__ float silu1(float g) { return g * __builtin_amdgcn_rcpf(1.0f + __expf(-g)); }
; __device__ __forceinline__ f32x4 swiglu4(f32x4 g, f32x4 u) { return (f32x4){silu1(g[0]) * u[0], silu1(g[1]) * u[1], silu1(g[2]) * u[2], silu1(g[3]) * u[3]}; }
; template <int EK>
; __device__ __forceinline__ void epi_tile(const f32x4 (&acc)[2][2][4][2], const Unit& u, int wr, int wc, int fr, int fq, const EpiArgs& E, const LAS float* rt) {
;     const int rowb = u.pm * BM + wr * 64 + fr;
;     float rr[2][4];
;     if (EK != EK_RES) {
; #pragma unroll
;         for (int ai = 0; ai < 2; ++ai)
; #pragma unroll
;             for (int m = 0; m < 4; ++m) rr[ai][m] = rt[ai * HALF + wr * 64 + m * 16 + fr];
;     }
; #pragma unroll
;     for (int ai = 0; ai < 2; ++ai) {
; #pragma unroll
;         for (int m = 0; m < 4; ++m) {
;             const int row = rowb + ai * HALF + m * 16;
;             if (EK == EK_SCALE) {
;                 const float r = rr[ai][m];
; #pragma unroll
;                 for (int bj = 0; bj < 2; ++bj) { const int col = u.pn * BM + bj * HALF + wc * 32 + fq * 8;
;                     const u32x2 lo = pack4(acc[ai][bj][m][0] * r), hi = pack4(acc[ai][bj][m][1] * r);
;                     *(u32x4*)(E.ob + (size_t)row * E.ldb + col) = (u32x4){lo.x, lo.y, hi.x, hi.y}; }
;             } else if (EK == EK_GELU) {
;                 const float r = rr[ai][m]; float ss = 0.f;
; #pragma unroll
;                 for (int bj = 0; bj < 2; ++bj) { const int col = u.pn * BM + bj * HALF + wc * 32 + fq * 8;
;                     const f32x4 z0 = gelu4(acc[ai][bj][m][0] * r), z1 = gelu4(acc[ai][bj][m][1] * r); ss += dot4(z0) + dot4(z1);
;                     const u32x2 lo = pack4(z0), hi = pack4(z1);
;                     *(u32x4*)(E.ob + (size_t)row * E.ldb + col) = (u32x4){lo.x, lo.y, hi.x, hi.y}; }
;                 if (u.pn >= 4) { ss = quad_sum(ss); if (fq == 0) E.stOut[(size_t)row * 16 + (u.pn - 4) * 4 + wc] = ss; }
;             } else if (EK == EK_SWIGLU) {
;                 const float r = rr[ai][m];
;                 { const int col = u.pn * HALF + wc * 32 + fq * 8;
;                     const u32x2 lo = pack4(swiglu4(acc[ai][0][m][0] * r, acc[ai][1][m][0] * r)), hi = pack4(swiglu4(acc[ai][0][m][1] * r, acc[ai][1][m][1] * r));
;                     *(u32x4*)(E.ob + (size_t)row * DFF + col) = (u32x4){lo.x, lo.y, hi.x, hi.y}; }
.LBB0_1248:
	v_lshl_add_u32 v146, s57, 10, v157
	ds_read2_b32 v[166:167], v146 offset1:16
	ds_read2_b32 v[154:155], v146 offset0:32 offset1:48
	ds_read2_b32 v[152:153], v146 offset0:128 offset1:144
	ds_read2_b32 v[146:147], v146 offset0:160 offset1:176
	v_lshl_or_b32 v150, s16, 7, v158
	s_waitcnt lgkmcnt(0)
	v_mul_f32_e32 v180, 0xbfb8aa3b, v166
	v_mul_f32_e32 v181, v166, v166
	v_rcp_f32_e32 v181, v181
	v_mul_f32_e32 v182, 0xbfb8aa3b, v167
	v_mul_f32_e32 v183, v167, v167
	v_rcp_f32_e32 v183, v183
	v_mul_f32_e32 v184, 0xbfb8aa3b, v154
	v_mul_f32_e32 v185, v154, v154
	v_rcp_f32_e32 v185, v185
	v_mul_f32_e32 v186, 0xbfb8aa3b, v155
	v_mul_f32_e32 v187, v155, v155
	v_rcp_f32_e32 v187, v187
	v_mul_f32_e32 v188, 0xbfb8aa3b, v152
	v_mul_f32_e32 v189, v152, v152
	v_rcp_f32_e32 v189, v189
	v_mul_f32_e32 v190, 0xbfb8aa3b, v153
	v_mul_f32_e32 v191, v153, v153
	v_rcp_f32_e32 v191, v191
	v_mul_f32_e32 v192, 0xbfb8aa3b, v146
	v_mul_f32_e32 v193, v146, v146
	v_rcp_f32_e32 v193, v193
	v_mul_f32_e32 v194, 0xbfb8aa3b, v147
	v_mul_f32_e32 v195, v147, v147
	v_rcp_f32_e32 v195, v195
	v_lshl_add_u32 v160, s18, 8, v1
	v_ashrrev_i32_e32 v151, 31, v150
	v_lshlrev_b64 v[150:151], 1, v[150:151]
	s_add_u32 s40, s59, 0xffffff00
	v_or_b32_e32 v172, 16, v160
	s_addc_u32 s41, s66, -1
	v_mov_b64_e32 v[148:149], s[64:65]
	v_mad_i64_i32 v[168:169], s[42:43], v160, s56, v[148:149]
	v_lshl_add_u64 v[168:169], v[168:169], 0, v[150:151]
	v_pk_mul_f32 v[196:197], v[110:111], v[180:181] op_sel_hi:[1,0]
	v_pk_mul_f32 v[198:199], v[112:113], v[180:181] op_sel_hi:[1,0]
	v_pk_mul_f32 v[200:201], v[110:111], v[78:79]
	v_exp_f32_e32 v196, v196
	v_exp_f32_e32 v197, v197
	v_exp_f32_e32 v198, v198
	v_exp_f32_e32 v199, v199
	v_pk_mul_f32 v[202:203], v[112:113], v[80:81]
	v_pk_fma_f32 v[196:197], v[196:197], v[180:181], v[180:181] op_sel:[0,1,1] op_sel_hi:[1,1,1]
	v_pk_fma_f32 v[198:199], v[198:199], v[180:181], v[180:181] op_sel:[0,1,1] op_sel_hi:[1,1,1]
	v_rcp_f32_e32 v196, v196
	v_rcp_f32_e32 v197, v197
	v_rcp_f32_e32 v198, v198
	v_rcp_f32_e32 v199, v199
	v_pk_mul_f32 v[200:201], v[200:201], v[196:197]
	v_pk_mul_f32 v[202:203], v[202:203], v[198:199]
	v_cvt_pk_bf16_f32 v204, v200, v201
	v_cvt_pk_bf16_f32 v205, v202, v203
	v_pk_mul_f32 v[196:197], v[106:107], v[180:181] op_sel_hi:[1,0]
	v_pk_mul_f32 v[198:199], v[108:109], v[180:181] op_sel_hi:[1,0]
	v_pk_mul_f32 v[200:201], v[106:107], v[74:75]
	v_exp_f32_e32 v196, v196
	v_exp_f32_e32 v197, v197
	v_exp_f32_e32 v198, v198
	v_exp_f32_e32 v199, v199
	v_pk_mul_f32 v[202:203], v[108:109], v[76:77]
	v_pk_fma_f32 v[196:197], v[196:197], v[180:181], v[180:181] op_sel:[0,1,1] op_sel_hi:[1,1,1]
	v_pk_fma_f32 v[198:199], v[198:199], v[180:181], v[180:181] op_sel:[0,1,1] op_sel_hi:[1,1,1]
	v_rcp_f32_e32 v196, v196
	v_rcp_f32_e32 v197, v197
	v_rcp_f32_e32 v198, v198
	v_rcp_f32_e32 v199, v199
	v_pk_mul_f32 v[200:201], v[200:201], v[196:197]
	v_pk_mul_f32 v[202:203], v[202:203], v[198:199]
	v_cvt_pk_bf16_f32 v206, v200, v201
	v_cvt_pk_bf16_f32 v207, v202, v203
	global_store_dwordx4 v[168:169], v[204:207], off
	s_andn2_b64 vcc, exec, s[6:7]
	v_mad_i64_i32 v[166:167], s[42:43], v172, s56, v[148:149]
	v_lshl_add_u64 v[166:167], v[166:167], 0, v[150:151]
	v_pk_mul_f32 v[196:197], v[102:103], v[182:183] op_sel_hi:[1,0]
	v_pk_mul_f32 v[198:199], v[104:105], v[182:183] op_sel_hi:[1,0]
	v_pk_mul_f32 v[200:201], v[102:103], v[70:71]
	v_exp_f32_e32 v196, v196
	v_exp_f32_e32 v197, v197
	v_exp_f32_e32 v198, v198
	v_exp_f32_e32 v199, v199
	v_pk_mul_f32 v[202:203], v[104:105], v[72:73]
	v_pk_fma_f32 v[196:197], v[196:197], v[182:183], v[182:183] op_sel:[0,1,1] op_sel_hi:[1,1,1]
	v_pk_fma_f32 v[198:199], v[198:199], v[182:183], v[182:183] op_sel:[0,1,1] op_sel_hi:[1,1,1]
	v_rcp_f32_e32 v196, v196
	v_rcp_f32_e32 v197, v197
	v_rcp_f32_e32 v198, v198
	v_rcp_f32_e32 v199, v199
	v_pk_mul_f32 v[200:201], v[200:201], v[196:197]
	v_pk_mul_f32 v[202:203], v[202:203], v[198:199]
	v_cvt_pk_bf16_f32 v208, v200, v201
	v_cvt_pk_bf16_f32 v209, v202, v203
	v_pk_mul_f32 v[196:197], v[98:99], v[182:183] op_sel_hi:[1,0]
	v_pk_mul_f32 v[198:199], v[100:101], v[182:183] op_sel_hi:[1,0]
	v_pk_mul_f32 v[200:201], v[98:99], v[66:67]
	v_exp_f32_e32 v196, v196
	v_exp_f32_e32 v197, v197
	v_exp_f32_e32 v198, v198
	v_exp_f32_e32 v199, v199
	v_pk_mul_f32 v[202:203], v[100:101], v[68:69]
	v_pk_fma_f32 v[196:197], v[196:197], v[182:183], v[182:183] op_sel:[0,1,1] op_sel_hi:[1,1,1]
	v_pk_fma_f32 v[198:199], v[198:199], v[182:183], v[182:183] op_sel:[0,1,1] op_sel_hi:[1,1,1]
	v_rcp_f32_e32 v196, v196
	v_rcp_f32_e32 v197, v197
	v_rcp_f32_e32 v198, v198
	v_rcp_f32_e32 v199, v199
	v_pk_mul_f32 v[200:201], v[200:201], v[196:197]
	v_pk_mul_f32 v[202:203], v[202:203], v[198:199]
	v_cvt_pk_bf16_f32 v210, v200, v201
	v_cvt_pk_bf16_f32 v211, v202, v203
	global_store_dwordx4 v[166:167], v[208:211], off
	v_or_b32_e32 v172, 32, v160
	v_mad_i64_i32 v[166:167], s[42:43], v172, s56, v[148:149]
	v_lshl_add_u64 v[166:167], v[166:167], 0, v[150:151]
	v_pk_mul_f32 v[196:197], v[94:95], v[184:185] op_sel_hi:[1,0]
	v_pk_mul_f32 v[198:199], v[96:97], v[184:185] op_sel_hi:[1,0]
	v_pk_mul_f32 v[200:201], v[94:95], v[62:63]
	v_exp_f32_e32 v196, v196
	v_exp_f32_e32 v197, v197
	v_exp_f32_e32 v198, v198
	v_exp_f32_e32 v199, v199
	v_pk_mul_f32 v[202:203], v[96:97], v[64:65]
	v_pk_fma_f32 v[196:197], v[196:197], v[184:185], v[184:185] op_sel:[0,1,1] op_sel_hi:[1,1,1]
	v_pk_fma_f32 v[198:199], v[198:199], v[184:185], v[184:185] op_sel:[0,1,1] op_sel_hi:[1,1,1]
	v_rcp_f32_e32 v196, v196
	v_rcp_f32_e32 v197, v197
	v_rcp_f32_e32 v198, v198
	v_rcp_f32_e32 v199, v199
	v_pk_mul_f32 v[200:201], v[200:201], v[196:197]
; __device__ __forceinline__ u32x2 pack4(f32x4 v) { u32x2 w; w.x = cvt_pk_bf16(v[0], v[1]); w.y = cvt_pk_bf16(v[2], v[3]); return w; }
; __device__ __forceinline__ float silu1(float g) { return g * __builtin_amdgcn_rcpf(1.0f + __expf(-g)); }
; __device__ __forceinline__ f32x4 swiglu4(f32x4 g, f32x4 u) { return (f32x4){silu1(g[0]) * u[0], silu1(g[1]) * u[1], silu1(g[2]) * u[2], silu1(g[3]) * u[3]}; }
; template <int EK>
; __device__ __forceinline__ void epi_tile(const f32x4 (&acc)[2][2][4][2], const Unit& u, int wr, int wc, int fr, int fq, const EpiArgs& E, const LAS float* rt) {
;     ...
;             } else if (EK == EK_SWIGLU) {
;                 const float r = rr[ai][m];
;                 { const int col = u.pn * HALF + wc * 32 + fq * 8;
;                     const u32x2 lo = pack4(swiglu4(acc[ai][0][m][0] * r, acc[ai][1][m][0] * r)), hi = pack4(swiglu4(acc[ai][0][m][1] * r, acc[ai][1][m][1] * r));
;                     *(u32x4*)(E.ob + (size_t)row * DFF + col) = (u32x4){lo.x, lo.y, hi.x, hi.y}; }
	v_pk_mul_f32 v[202:203], v[202:203], v[198:199]
	v_cvt_pk_bf16_f32 v204, v200, v201
	v_cvt_pk_bf16_f32 v205, v202, v203
	v_pk_mul_f32 v[196:197], v[90:91], v[184:185] op_sel_hi:[1,0]
	v_pk_mul_f32 v[198:199], v[92:93], v[184:185] op_sel_hi:[1,0]
	v_pk_mul_f32 v[200:201], v[90:91], v[58:59]
	v_exp_f32_e32 v196, v196
	v_exp_f32_e32 v197, v197
	v_exp_f32_e32 v198, v198
	v_exp_f32_e32 v199, v199
	v_pk_mul_f32 v[202:203], v[92:93], v[60:61]
	v_pk_fma_f32 v[196:197], v[196:197], v[184:185], v[184:185] op_sel:[0,1,1] op_sel_hi:[1,1,1]
	v_pk_fma_f32 v[198:199], v[198:199], v[184:185], v[184:185] op_sel:[0,1,1] op_sel_hi:[1,1,1]
	v_rcp_f32_e32 v196, v196
	v_rcp_f32_e32 v197, v197
	v_rcp_f32_e32 v198, v198
	v_rcp_f32_e32 v199, v199
	v_pk_mul_f32 v[200:201], v[200:201], v[196:197]
	v_pk_mul_f32 v[202:203], v[202:203], v[198:199]
	v_cvt_pk_bf16_f32 v206, v200, v201
	v_cvt_pk_bf16_f32 v207, v202, v203
	global_store_dwordx4 v[166:167], v[204:207], off
	v_or_b32_e32 v161, 48, v160
	v_mad_i64_i32 v[154:155], s[42:43], v161, s56, v[148:149]
	v_lshl_add_u64 v[154:155], v[154:155], 0, v[150:151]
	v_pk_mul_f32 v[196:197], v[86:87], v[186:187] op_sel_hi:[1,0]
	v_pk_mul_f32 v[198:199], v[88:89], v[186:187] op_sel_hi:[1,0]
	v_pk_mul_f32 v[200:201], v[86:87], v[54:55]
	v_exp_f32_e32 v196, v196
	v_exp_f32_e32 v197, v197
	v_exp_f32_e32 v198, v198
	v_exp_f32_e32 v199, v199
	v_pk_mul_f32 v[202:203], v[88:89], v[56:57]
	v_pk_fma_f32 v[196:197], v[196:197], v[186:187], v[186:187] op_sel:[0,1,1] op_sel_hi:[1,1,1]
	v_pk_fma_f32 v[198:199], v[198:199], v[186:187], v[186:187] op_sel:[0,1,1] op_sel_hi:[1,1,1]
	v_rcp_f32_e32 v196, v196
	v_rcp_f32_e32 v197, v197
	v_rcp_f32_e32 v198, v198
	v_rcp_f32_e32 v199, v199
	v_pk_mul_f32 v[200:201], v[200:201], v[196:197]
	v_pk_mul_f32 v[202:203], v[202:203], v[198:199]
	v_cvt_pk_bf16_f32 v208, v200, v201
	v_cvt_pk_bf16_f32 v209, v202, v203
	v_pk_mul_f32 v[196:197], v[82:83], v[186:187] op_sel_hi:[1,0]
	v_pk_mul_f32 v[198:199], v[84:85], v[186:187] op_sel_hi:[1,0]
	v_pk_mul_f32 v[200:201], v[82:83], v[50:51]
	v_exp_f32_e32 v196, v196
	v_exp_f32_e32 v197, v197
	v_exp_f32_e32 v198, v198
	v_exp_f32_e32 v199, v199
	v_pk_mul_f32 v[202:203], v[84:85], v[52:53]
	v_pk_fma_f32 v[196:197], v[196:197], v[186:187], v[186:187] op_sel:[0,1,1] op_sel_hi:[1,1,1]
	v_pk_fma_f32 v[198:199], v[198:199], v[186:187], v[186:187] op_sel:[0,1,1] op_sel_hi:[1,1,1]
	v_rcp_f32_e32 v196, v196
	v_rcp_f32_e32 v197, v197
	v_rcp_f32_e32 v198, v198
	v_rcp_f32_e32 v199, v199
	v_pk_mul_f32 v[200:201], v[200:201], v[196:197]
	v_pk_mul_f32 v[202:203], v[202:203], v[198:199]
	v_cvt_pk_bf16_f32 v210, v200, v201
	v_cvt_pk_bf16_f32 v211, v202, v203
	global_store_dwordx4 v[154:155], v[208:211], off
	v_add_u32_e32 v170, 0x80, v160
	v_mad_i64_i32 v[154:155], s[42:43], v170, s56, v[148:149]
	v_lshl_add_u64 v[154:155], v[154:155], 0, v[150:151]
	v_pk_mul_f32 v[196:197], v[46:47], v[188:189] op_sel_hi:[1,0]
	v_pk_mul_f32 v[198:199], v[48:49], v[188:189] op_sel_hi:[1,0]
	v_pk_mul_f32 v[200:201], v[46:47], v[14:15]
	v_exp_f32_e32 v196, v196
	v_exp_f32_e32 v197, v197
	v_exp_f32_e32 v198, v198
	v_exp_f32_e32 v199, v199
	v_pk_mul_f32 v[202:203], v[48:49], v[16:17]
	v_pk_fma_f32 v[196:197], v[196:197], v[188:189], v[188:189] op_sel:[0,1,1] op_sel_hi:[1,1,1]
	v_pk_fma_f32 v[198:199], v[198:199], v[188:189], v[188:189] op_sel:[0,1,1] op_sel_hi:[1,1,1]
	v_rcp_f32_e32 v196, v196
	v_rcp_f32_e32 v197, v197
	v_rcp_f32_e32 v198, v198
	v_rcp_f32_e32 v199, v199
	v_pk_mul_f32 v[200:201], v[200:201], v[196:197]
	v_pk_mul_f32 v[202:203], v[202:203], v[198:199]
	v_cvt_pk_bf16_f32 v204, v200, v201
	v_cvt_pk_bf16_f32 v205, v202, v203
	v_pk_mul_f32 v[196:197], v[42:43], v[188:189] op_sel_hi:[1,0]
	v_pk_mul_f32 v[198:199], v[44:45], v[188:189] op_sel_hi:[1,0]
	v_pk_mul_f32 v[200:201], v[42:43], v[10:11]
	v_exp_f32_e32 v196, v196
	v_exp_f32_e32 v197, v197
	v_exp_f32_e32 v198, v198
	v_exp_f32_e32 v199, v199
	v_pk_mul_f32 v[202:203], v[44:45], v[12:13]
	v_pk_fma_f32 v[196:197], v[196:197], v[188:189], v[188:189] op_sel:[0,1,1] op_sel_hi:[1,1,1]
	v_pk_fma_f32 v[198:199], v[198:199], v[188:189], v[188:189] op_sel:[0,1,1] op_sel_hi:[1,1,1]
	v_rcp_f32_e32 v196, v196
	v_rcp_f32_e32 v197, v197
	v_rcp_f32_e32 v198, v198
	v_rcp_f32_e32 v199, v199
	v_pk_mul_f32 v[200:201], v[200:201], v[196:197]
	v_pk_mul_f32 v[202:203], v[202:203], v[198:199]
	v_cvt_pk_bf16_f32 v206, v200, v201
	v_cvt_pk_bf16_f32 v207, v202, v203
	global_store_dwordx4 v[154:155], v[204:207], off
	v_add_u32_e32 v161, 0x90, v160
	v_mad_i64_i32 v[162:163], s[42:43], v161, s56, v[148:149]
	v_lshl_add_u64 v[162:163], v[162:163], 0, v[150:151]
	v_pk_mul_f32 v[196:197], v[38:39], v[190:191] op_sel_hi:[1,0]
	v_pk_mul_f32 v[198:199], v[40:41], v[190:191] op_sel_hi:[1,0]
	v_pk_mul_f32 v[200:201], v[38:39], v[6:7]
	v_exp_f32_e32 v196, v196
	v_exp_f32_e32 v197, v197
	v_exp_f32_e32 v198, v198
	v_exp_f32_e32 v199, v199
	v_pk_mul_f32 v[202:203], v[40:41], v[8:9]
; __device__ __forceinline__ u32x2 pack4(f32x4 v) { u32x2 w; w.x = cvt_pk_bf16(v[0], v[1]); w.y = cvt_pk_bf16(v[2], v[3]); return w; }
; __device__ __forceinline__ f32x4 swiglu4(f32x4 g, f32x4 u) { return (f32x4){silu1(g[0]) * u[0], silu1(g[1]) * u[1], silu1(g[2]) * u[2], silu1(g[3]) * u[3]}; }
; #define PG8_BAR __builtin_amdgcn_s_barrier()
; template <int EK>
; __device__ __forceinline__ void epi_tile(const f32x4 (&acc)[2][2][4][2], const Unit& u, int wr, int wc, int fr, int fq, const EpiArgs& E, const LAS float* rt) {
;     ...
;             } else if (EK == EK_SWIGLU) {
;                 const float r = rr[ai][m];
;                 { const int col = u.pn * HALF + wc * 32 + fq * 8;
;                     const u32x2 lo = pack4(swiglu4(acc[ai][0][m][0] * r, acc[ai][1][m][0] * r)), hi = pack4(swiglu4(acc[ai][0][m][1] * r, acc[ai][1][m][1] * r));
;                     *(u32x4*)(E.ob + (size_t)row * DFF + col) = (u32x4){lo.x, lo.y, hi.x, hi.y}; }
; template <int EK, int SK = -1>
; __device__ __forceinline__ void gemm_phase(LAS unsigned char* lds, const bf16_t* A, const bf16_t* Bt, int nM, int N, int K, const EpiArgs& E) {
;     ...
;         if (!has_next) break;
; #pragma unroll
;         for (int a = 0; a < 2; ++a)
; #pragma unroll
;             for (int b = 0; b < 2; ++b)
; #pragma unroll
;                 for (int m = 0; m < 4; ++m)
; #pragma unroll
;                     for (int n = 0; n < 2; ++n) acc[a][b][m][n] = (f32x4){0.f, 0.f, 0.f, 0.f};
;         cur = nxt; cA = nA; cB = nB; ++ui;
;         if (wr == 1) PG8_BAR;
	v_pk_fma_f32 v[196:197], v[196:197], v[190:191], v[190:191] op_sel:[0,1,1] op_sel_hi:[1,1,1]
	v_pk_fma_f32 v[198:199], v[198:199], v[190:191], v[190:191] op_sel:[0,1,1] op_sel_hi:[1,1,1]
	v_rcp_f32_e32 v196, v196
	v_rcp_f32_e32 v197, v197
	v_rcp_f32_e32 v198, v198
	v_rcp_f32_e32 v199, v199
	v_pk_mul_f32 v[200:201], v[200:201], v[196:197]
	v_pk_mul_f32 v[202:203], v[202:203], v[198:199]
	v_cvt_pk_bf16_f32 v208, v200, v201
	v_cvt_pk_bf16_f32 v209, v202, v203
	v_pk_mul_f32 v[196:197], v[34:35], v[190:191] op_sel_hi:[1,0]
	v_pk_mul_f32 v[198:199], v[36:37], v[190:191] op_sel_hi:[1,0]
	v_pk_mul_f32 v[200:201], v[34:35], v[2:3]
	v_exp_f32_e32 v196, v196
	v_exp_f32_e32 v197, v197
	v_exp_f32_e32 v198, v198
	v_exp_f32_e32 v199, v199
	v_pk_mul_f32 v[202:203], v[36:37], v[4:5]
	v_pk_fma_f32 v[196:197], v[196:197], v[190:191], v[190:191] op_sel:[0,1,1] op_sel_hi:[1,1,1]
	v_pk_fma_f32 v[198:199], v[198:199], v[190:191], v[190:191] op_sel:[0,1,1] op_sel_hi:[1,1,1]
	v_rcp_f32_e32 v196, v196
	v_rcp_f32_e32 v197, v197
	v_rcp_f32_e32 v198, v198
	v_rcp_f32_e32 v199, v199
	v_pk_mul_f32 v[200:201], v[200:201], v[196:197]
	v_pk_mul_f32 v[202:203], v[202:203], v[198:199]
	v_cvt_pk_bf16_f32 v210, v200, v201
	v_cvt_pk_bf16_f32 v211, v202, v203
	global_store_dwordx4 v[162:163], v[208:211], off
	v_add_u32_e32 v168, 0xa0, v160
	v_mad_i64_i32 v[162:163], s[42:43], v168, s56, v[148:149]
	v_lshl_add_u64 v[162:163], v[162:163], 0, v[150:151]
	v_pk_mul_f32 v[196:197], v[30:31], v[192:193] op_sel_hi:[1,0]
	v_pk_mul_f32 v[198:199], v[32:33], v[192:193] op_sel_hi:[1,0]
	v_pk_mul_f32 v[200:201], v[30:31], v[114:115]
	v_exp_f32_e32 v196, v196
	v_exp_f32_e32 v197, v197
	v_exp_f32_e32 v198, v198
	v_exp_f32_e32 v199, v199
	v_pk_mul_f32 v[202:203], v[32:33], v[116:117]
	v_pk_fma_f32 v[196:197], v[196:197], v[192:193], v[192:193] op_sel:[0,1,1] op_sel_hi:[1,1,1]
	v_pk_fma_f32 v[198:199], v[198:199], v[192:193], v[192:193] op_sel:[0,1,1] op_sel_hi:[1,1,1]
	v_rcp_f32_e32 v196, v196
	v_rcp_f32_e32 v197, v197
	v_rcp_f32_e32 v198, v198
	v_rcp_f32_e32 v199, v199
	v_pk_mul_f32 v[200:201], v[200:201], v[196:197]
	v_pk_mul_f32 v[202:203], v[202:203], v[198:199]
	v_cvt_pk_bf16_f32 v204, v200, v201
	v_cvt_pk_bf16_f32 v205, v202, v203
	v_pk_mul_f32 v[196:197], v[26:27], v[192:193] op_sel_hi:[1,0]
	v_pk_mul_f32 v[198:199], v[28:29], v[192:193] op_sel_hi:[1,0]
	v_pk_mul_f32 v[200:201], v[26:27], v[118:119]
	v_exp_f32_e32 v196, v196
	v_exp_f32_e32 v197, v197
	v_exp_f32_e32 v198, v198
	v_exp_f32_e32 v199, v199
	v_pk_mul_f32 v[202:203], v[28:29], v[120:121]
	v_pk_fma_f32 v[196:197], v[196:197], v[192:193], v[192:193] op_sel:[0,1,1] op_sel_hi:[1,1,1]
	v_pk_fma_f32 v[198:199], v[198:199], v[192:193], v[192:193] op_sel:[0,1,1] op_sel_hi:[1,1,1]
	v_rcp_f32_e32 v196, v196
	v_rcp_f32_e32 v197, v197
	v_rcp_f32_e32 v198, v198
	v_rcp_f32_e32 v199, v199
	v_pk_mul_f32 v[200:201], v[200:201], v[196:197]
	v_pk_mul_f32 v[202:203], v[202:203], v[198:199]
	v_cvt_pk_bf16_f32 v206, v200, v201
	v_cvt_pk_bf16_f32 v207, v202, v203
	global_store_dwordx4 v[162:163], v[204:207], off
	v_add_u32_e32 v164, 0xb0, v160
	v_mad_i64_i32 v[146:147], s[42:43], v164, s56, v[148:149]
	v_lshl_add_u64 v[146:147], v[146:147], 0, v[150:151]
	v_pk_mul_f32 v[196:197], v[22:23], v[194:195] op_sel_hi:[1,0]
	v_pk_mul_f32 v[198:199], v[24:25], v[194:195] op_sel_hi:[1,0]
	v_pk_mul_f32 v[200:201], v[22:23], v[122:123]
	v_exp_f32_e32 v196, v196
	v_exp_f32_e32 v197, v197
	v_exp_f32_e32 v198, v198
	v_exp_f32_e32 v199, v199
	v_pk_mul_f32 v[202:203], v[24:25], v[124:125]
	v_pk_fma_f32 v[196:197], v[196:197], v[194:195], v[194:195] op_sel:[0,1,1] op_sel_hi:[1,1,1]
	v_pk_fma_f32 v[198:199], v[198:199], v[194:195], v[194:195] op_sel:[0,1,1] op_sel_hi:[1,1,1]
	v_rcp_f32_e32 v196, v196
	v_rcp_f32_e32 v197, v197
	v_rcp_f32_e32 v198, v198
	v_rcp_f32_e32 v199, v199
	v_pk_mul_f32 v[200:201], v[200:201], v[196:197]
	v_pk_mul_f32 v[202:203], v[202:203], v[198:199]
	v_cvt_pk_bf16_f32 v208, v200, v201
	v_cvt_pk_bf16_f32 v209, v202, v203
	v_pk_mul_f32 v[196:197], v[18:19], v[194:195] op_sel_hi:[1,0]
	v_pk_mul_f32 v[198:199], v[20:21], v[194:195] op_sel_hi:[1,0]
	v_pk_mul_f32 v[200:201], v[18:19], v[126:127]
	v_exp_f32_e32 v196, v196
	v_exp_f32_e32 v197, v197
	v_exp_f32_e32 v198, v198
	v_exp_f32_e32 v199, v199
	v_pk_mul_f32 v[202:203], v[20:21], v[128:129]
	v_pk_fma_f32 v[196:197], v[196:197], v[194:195], v[194:195] op_sel:[0,1,1] op_sel_hi:[1,1,1]
	v_pk_fma_f32 v[198:199], v[198:199], v[194:195], v[194:195] op_sel:[0,1,1] op_sel_hi:[1,1,1]
	v_rcp_f32_e32 v196, v196
	v_rcp_f32_e32 v197, v197
	v_rcp_f32_e32 v198, v198
	v_rcp_f32_e32 v199, v199
	v_pk_mul_f32 v[200:201], v[200:201], v[196:197]
	v_pk_mul_f32 v[202:203], v[202:203], v[198:199]
	v_cvt_pk_bf16_f32 v210, v200, v201
	v_cvt_pk_bf16_f32 v211, v202, v203
	global_store_dwordx4 v[146:147], v[208:211], off
	s_cbranch_vccnz .LBB0_1251
	s_andn2_b64 vcc, exec, s[8:9]
	s_cbranch_vccnz .LBB0_1237
	s_barrier
	s_branch .LBB0_1237
